# a1 + XCD-local grid barriers for B2,B9,B10,B12 (runtime XCD-affinity census; full barrier fallback)
# speedup vs baseline: 1.0053x; 1.0053x over previous
_Z10fwd_kernel6Params:
	s_load_dwordx8 s[20:27], s[0:1], 0x80
	s_load_dword s30, s[0:1], 0xa8
	s_load_dwordx2 s[28:29], s[0:1], 0xa0
	s_add_u32 s6, s0, 0xa0
	v_and_b32_e32 v1, 0x3ff, v0
	s_addc_u32 s7, s1, 0
	v_cmp_gt_u32_e32 vcc, 2, v1
	s_and_saveexec_b64 s[4:5], vcc
	v_lshl_add_u32 v2, v1, 2, 0
	v_add_u32_e32 v2, 0x20000, v2
	v_mov_b32_e32 v3, 0
	ds_write_b32 v2, v3
	s_or_b64 exec, exec, s[4:5]
	s_waitcnt lgkmcnt(0)
	s_add_u32 s94, s26, 0xfe00000
	s_barrier
	s_getreg_b32 s3, hwreg(HW_REG_XCC_ID, 0, 4)
	s_addc_u32 s95, s27, 0
	s_and_b32 s84, s3, 15
	v_cmp_eq_u32_e64 s[8:9], 0, v1
	s_mov_b64 s[4:5], exec
	s_nop 0
	v_writelane_b32 v248, s8, 0
	s_nop 1
	v_writelane_b32 v248, s9, 1
	s_and_b64 s[8:9], s[4:5], s[8:9]
	s_mov_b64 exec, s[8:9]
	s_cbranch_execz .LBB0_5
	s_mov_b64 s[10:11], exec
	v_mbcnt_lo_u32_b32 v2, s10, 0
	v_mbcnt_hi_u32_b32 v2, s11, v2
	v_cmp_eq_u32_e32 vcc, 0, v2
	s_and_b64 s[8:9], exec, vcc
	s_mov_b64 exec, s[8:9]
	s_cbranch_execz .LBB0_5
	s_lshl_b32 s3, s84, 8
	s_bcnt1_i32_b64 s8, s[10:11]
	v_mov_b32_e32 v2, s3
	v_mov_b32_e32 v3, s8
	s_and_b32 s12, s2, 7
	s_lshl_b32 s12, 1, s12
	v_mov_b32_e32 v5, s12
	s_lshl_b32 s13, s84, 6
	v_mov_b32_e32 v6, s13
	v_add_u32_e32 v6, 0x3800, v6
	global_atomic_or v6, v5, s[94:95]
	s_waitcnt vmcnt(0)
	global_atomic_add v2, v3, s[94:95] offset:1024

.LBB0_241:
	s_cmp_eq_u32 s84, 0
	s_cselect_b64 vcc, -1, 0
	s_cmp_eq_u32 s84, 1
	v_cndmask_b32_e32 v16, 0, v15, vcc
	s_cselect_b64 vcc, -1, 0
	s_cmp_eq_u32 s84, 2
	v_cndmask_b32_e32 v16, v16, v0, vcc
	s_cselect_b64 vcc, -1, 0
	s_cmp_eq_u32 s84, 3
	v_cndmask_b32_e32 v16, v16, v1, vcc
	s_cselect_b64 vcc, -1, 0
	s_cmp_eq_u32 s84, 4
	v_cndmask_b32_e32 v16, v16, v2, vcc
	s_cselect_b64 vcc, -1, 0
	s_cmp_eq_u32 s84, 5
	v_cndmask_b32_e32 v16, v16, v3, vcc
	s_cselect_b64 vcc, -1, 0
	s_cmp_eq_u32 s84, 6
	v_cndmask_b32_e32 v16, v16, v4, vcc
	s_cselect_b64 vcc, -1, 0
	s_cmp_eq_u32 s84, 7
	v_cndmask_b32_e32 v16, v16, v5, vcc
	s_cselect_b64 vcc, -1, 0
	s_cmp_eq_u32 s84, 8
	v_cndmask_b32_e32 v16, v16, v6, vcc
	s_cselect_b64 vcc, -1, 0
	s_cmp_eq_u32 s84, 9
	v_cndmask_b32_e32 v16, v16, v7, vcc
	s_cselect_b64 vcc, -1, 0
	s_cmp_eq_u32 s84, 10
	v_cndmask_b32_e32 v16, v16, v8, vcc
	s_cselect_b64 vcc, -1, 0
	s_cmp_eq_u32 s84, 11
	v_cndmask_b32_e32 v16, v16, v9, vcc
	s_cselect_b64 vcc, -1, 0
	s_cmp_eq_u32 s84, 12
	v_cndmask_b32_e32 v16, v16, v10, vcc
	s_cselect_b64 vcc, -1, 0
	s_cmp_eq_u32 s84, 13
	v_cndmask_b32_e32 v16, v16, v11, vcc
	s_cselect_b64 vcc, -1, 0
	s_cmp_eq_u32 s84, 14
	v_cndmask_b32_e32 v16, v16, v12, vcc
	s_cselect_b64 vcc, -1, 0
	s_cmp_eq_u32 s84, 15
	v_cndmask_b32_e32 v16, v16, v13, vcc
	s_cselect_b64 vcc, -1, 0
	v_cndmask_b32_e32 v16, v16, v14, vcc
	v_cmp_ne_u32_e32 vcc, 0, v15
	s_add_i32 s4, 0, 0x20000
	s_nop 0
	v_cndmask_b32_e64 v15, 0, 1, vcc
	v_cmp_ne_u32_e32 vcc, 0, v0
	s_nop 1
	v_addc_co_u32_e32 v0, vcc, 0, v15, vcc
	v_cmp_ne_u32_e32 vcc, 0, v1
	s_nop 1
	v_cndmask_b32_e64 v1, 0, 1, vcc
	v_cmp_ne_u32_e32 vcc, 0, v2
	v_max_u32_e32 v2, 1, v16
	s_nop 0
	v_addc_co_u32_e32 v0, vcc, v0, v1, vcc
	v_cmp_ne_u32_e32 vcc, 0, v3
	s_nop 1
	v_cndmask_b32_e64 v1, 0, 1, vcc
	v_cmp_ne_u32_e32 vcc, 0, v4
	s_nop 1
	v_addc_co_u32_e32 v0, vcc, v0, v1, vcc
	v_cmp_ne_u32_e32 vcc, 0, v5
	s_nop 1
	v_cndmask_b32_e64 v1, 0, 1, vcc
	v_cmp_ne_u32_e32 vcc, 0, v6
	s_nop 1
	v_addc_co_u32_e32 v0, vcc, v0, v1, vcc
	v_cmp_ne_u32_e32 vcc, 0, v7
	s_nop 1
	v_cndmask_b32_e64 v1, 0, 1, vcc
	v_cmp_ne_u32_e32 vcc, 0, v8
	s_nop 1
	v_addc_co_u32_e32 v0, vcc, v0, v1, vcc
	v_cmp_ne_u32_e32 vcc, 0, v9
	s_nop 1
	v_cndmask_b32_e64 v1, 0, 1, vcc
	v_cmp_ne_u32_e32 vcc, 0, v10
	s_nop 1
	v_addc_co_u32_e32 v0, vcc, v0, v1, vcc
	v_cmp_ne_u32_e32 vcc, 0, v11
	s_nop 1
	v_cndmask_b32_e64 v1, 0, 1, vcc
	v_cmp_ne_u32_e32 vcc, 0, v12
	s_nop 1
	v_addc_co_u32_e32 v0, vcc, v0, v1, vcc
	v_cmp_ne_u32_e32 vcc, 0, v13
	s_nop 1
	v_cndmask_b32_e64 v1, 0, 1, vcc
	v_cmp_ne_u32_e32 vcc, 0, v14
	s_nop 1
	v_addc_co_u32_e32 v0, vcc, v0, v1, vcc
	v_mov_b32_e32 v1, s4
	s_add_i32 s4, 0, 0x20004
	v_max_u32_e32 v0, 1, v0
	ds_write_b32 v1, v2
	v_mov_b32_e32 v1, s4
	ds_write_b32 v1, v0
	v_mov_b32_e32 v4, 0
	v_mov_b32_e32 v5, 0x3800
	v_mov_b32_e32 v6, 0x1000
	global_load_dword v7, v4, s[30:31] offset:1024 sc1
	global_load_dword v8, v4, s[30:31] offset:1280 sc1
	global_load_dword v9, v4, s[30:31] offset:1536 sc1
	global_load_dword v10, v4, s[30:31] offset:1792 sc1
	global_load_dword v11, v4, s[30:31] offset:2048 sc1
	global_load_dword v12, v4, s[30:31] offset:2304 sc1
	global_load_dword v13, v4, s[30:31] offset:2560 sc1
	global_load_dword v14, v4, s[30:31] offset:2816 sc1
	global_load_dword v15, v4, s[30:31] offset:3072 sc1
	global_load_dword v16, v4, s[30:31] offset:3328 sc1
	global_load_dword v17, v4, s[30:31] offset:3584 sc1
	global_load_dword v18, v4, s[30:31] offset:3840 sc1
	global_load_dword v19, v6, s[30:31] offset:0 sc1
	global_load_dword v20, v6, s[30:31] offset:256 sc1
	global_load_dword v21, v6, s[30:31] offset:512 sc1
	global_load_dword v22, v6, s[30:31] offset:768 sc1
	global_load_dword v23, v5, s[30:31] offset:0 sc1
	global_load_dword v24, v5, s[30:31] offset:64 sc1
	global_load_dword v25, v5, s[30:31] offset:128 sc1
	global_load_dword v26, v5, s[30:31] offset:192 sc1
	global_load_dword v27, v5, s[30:31] offset:256 sc1
	global_load_dword v34, v5, s[30:31] offset:320 sc1
	global_load_dword v35, v5, s[30:31] offset:384 sc1
	global_load_dword v36, v5, s[30:31] offset:448 sc1
	global_load_dword v37, v5, s[30:31] offset:512 sc1
	global_load_dword v38, v5, s[30:31] offset:576 sc1
	global_load_dword v39, v5, s[30:31] offset:640 sc1
	global_load_dword v40, v5, s[30:31] offset:704 sc1
	global_load_dword v41, v5, s[30:31] offset:768 sc1
	global_load_dword v42, v5, s[30:31] offset:832 sc1
	global_load_dword v43, v5, s[30:31] offset:896 sc1
	global_load_dword v44, v5, s[30:31] offset:960 sc1
	s_waitcnt vmcnt(0)
	s_mov_b32 s8, 1
	s_lshr_b32 s11, s28, 3
	v_readfirstlane_b32 s9, v7
	v_readfirstlane_b32 s10, v23
	s_nop 3
	s_bcnt1_i32_b32 s10, s10
	s_cmp_eq_u32 s9, s11
	s_cselect_b32 s12, 1, 0
	s_cmp_eq_u32 s10, 1
	s_cselect_b32 s10, s12, 0
	s_cmp_eq_u32 s9, 0
	s_cselect_b32 s10, 1, s10
	s_and_b32 s8, s8, s10
	v_readfirstlane_b32 s9, v8
	v_readfirstlane_b32 s10, v24
	s_nop 3
	s_bcnt1_i32_b32 s10, s10
	s_cmp_eq_u32 s9, s11
	s_cselect_b32 s12, 1, 0
	s_cmp_eq_u32 s10, 1
	s_cselect_b32 s10, s12, 0
	s_cmp_eq_u32 s9, 0
	s_cselect_b32 s10, 1, s10
	s_and_b32 s8, s8, s10
	v_readfirstlane_b32 s9, v9
	v_readfirstlane_b32 s10, v25
	s_nop 3
	s_bcnt1_i32_b32 s10, s10
	s_cmp_eq_u32 s9, s11
	s_cselect_b32 s12, 1, 0
	s_cmp_eq_u32 s10, 1
	s_cselect_b32 s10, s12, 0
	s_cmp_eq_u32 s9, 0
	s_cselect_b32 s10, 1, s10
	s_and_b32 s8, s8, s10
	v_readfirstlane_b32 s9, v10
	v_readfirstlane_b32 s10, v26
	s_nop 3
	s_bcnt1_i32_b32 s10, s10
	s_cmp_eq_u32 s9, s11
	s_cselect_b32 s12, 1, 0
	s_cmp_eq_u32 s10, 1
	s_cselect_b32 s10, s12, 0
	s_cmp_eq_u32 s9, 0
	s_cselect_b32 s10, 1, s10
	s_and_b32 s8, s8, s10
	v_readfirstlane_b32 s9, v11
	v_readfirstlane_b32 s10, v27
	s_nop 3
	s_bcnt1_i32_b32 s10, s10
	s_cmp_eq_u32 s9, s11
	s_cselect_b32 s12, 1, 0
	s_cmp_eq_u32 s10, 1
	s_cselect_b32 s10, s12, 0
	s_cmp_eq_u32 s9, 0
	s_cselect_b32 s10, 1, s10
	s_and_b32 s8, s8, s10
	v_readfirstlane_b32 s9, v12
	v_readfirstlane_b32 s10, v34
	s_nop 3
	s_bcnt1_i32_b32 s10, s10
	s_cmp_eq_u32 s9, s11
	s_cselect_b32 s12, 1, 0
	s_cmp_eq_u32 s10, 1
	s_cselect_b32 s10, s12, 0
	s_cmp_eq_u32 s9, 0
	s_cselect_b32 s10, 1, s10
	s_and_b32 s8, s8, s10
	v_readfirstlane_b32 s9, v13
	v_readfirstlane_b32 s10, v35
	s_nop 3
	s_bcnt1_i32_b32 s10, s10
	s_cmp_eq_u32 s9, s11
	s_cselect_b32 s12, 1, 0
	s_cmp_eq_u32 s10, 1
	s_cselect_b32 s10, s12, 0
	s_cmp_eq_u32 s9, 0
	s_cselect_b32 s10, 1, s10
	s_and_b32 s8, s8, s10
	v_readfirstlane_b32 s9, v14
	v_readfirstlane_b32 s10, v36
	s_nop 3
	s_bcnt1_i32_b32 s10, s10
	s_cmp_eq_u32 s9, s11
	s_cselect_b32 s12, 1, 0
	s_cmp_eq_u32 s10, 1
	s_cselect_b32 s10, s12, 0
	s_cmp_eq_u32 s9, 0
	s_cselect_b32 s10, 1, s10
	s_and_b32 s8, s8, s10
	v_readfirstlane_b32 s9, v15
	v_readfirstlane_b32 s10, v37
	s_nop 3
	s_bcnt1_i32_b32 s10, s10
	s_cmp_eq_u32 s9, s11
	s_cselect_b32 s12, 1, 0
	s_cmp_eq_u32 s10, 1
	s_cselect_b32 s10, s12, 0
	s_cmp_eq_u32 s9, 0
	s_cselect_b32 s10, 1, s10
	s_and_b32 s8, s8, s10
	v_readfirstlane_b32 s9, v16
	v_readfirstlane_b32 s10, v38
	s_nop 3
	s_bcnt1_i32_b32 s10, s10
	s_cmp_eq_u32 s9, s11
	s_cselect_b32 s12, 1, 0
	s_cmp_eq_u32 s10, 1
	s_cselect_b32 s10, s12, 0
	s_cmp_eq_u32 s9, 0
	s_cselect_b32 s10, 1, s10
	s_and_b32 s8, s8, s10
	v_readfirstlane_b32 s9, v17
	v_readfirstlane_b32 s10, v39
	s_nop 3
	s_bcnt1_i32_b32 s10, s10
	s_cmp_eq_u32 s9, s11
	s_cselect_b32 s12, 1, 0
	s_cmp_eq_u32 s10, 1
	s_cselect_b32 s10, s12, 0
	s_cmp_eq_u32 s9, 0
	s_cselect_b32 s10, 1, s10
	s_and_b32 s8, s8, s10
	v_readfirstlane_b32 s9, v18
	v_readfirstlane_b32 s10, v40
	s_nop 3
	s_bcnt1_i32_b32 s10, s10
	s_cmp_eq_u32 s9, s11
	s_cselect_b32 s12, 1, 0
	s_cmp_eq_u32 s10, 1
	s_cselect_b32 s10, s12, 0
	s_cmp_eq_u32 s9, 0
	s_cselect_b32 s10, 1, s10
	s_and_b32 s8, s8, s10
	v_readfirstlane_b32 s9, v19
	v_readfirstlane_b32 s10, v41
	s_nop 3
	s_bcnt1_i32_b32 s10, s10
	s_cmp_eq_u32 s9, s11
	s_cselect_b32 s12, 1, 0
	s_cmp_eq_u32 s10, 1
	s_cselect_b32 s10, s12, 0
	s_cmp_eq_u32 s9, 0
	s_cselect_b32 s10, 1, s10
	s_and_b32 s8, s8, s10
	v_readfirstlane_b32 s9, v20
	v_readfirstlane_b32 s10, v42
	s_nop 3
	s_bcnt1_i32_b32 s10, s10
	s_cmp_eq_u32 s9, s11
	s_cselect_b32 s12, 1, 0
	s_cmp_eq_u32 s10, 1
	s_cselect_b32 s10, s12, 0
	s_cmp_eq_u32 s9, 0
	s_cselect_b32 s10, 1, s10
	s_and_b32 s8, s8, s10
	v_readfirstlane_b32 s9, v21
	v_readfirstlane_b32 s10, v43
	s_nop 3
	s_bcnt1_i32_b32 s10, s10
	s_cmp_eq_u32 s9, s11
	s_cselect_b32 s12, 1, 0
	s_cmp_eq_u32 s10, 1
	s_cselect_b32 s10, s12, 0
	s_cmp_eq_u32 s9, 0
	s_cselect_b32 s10, 1, s10
	s_and_b32 s8, s8, s10
	v_readfirstlane_b32 s9, v22
	v_readfirstlane_b32 s10, v44
	s_nop 3
	s_bcnt1_i32_b32 s10, s10
	s_cmp_eq_u32 s9, s11
	s_cselect_b32 s12, 1, 0
	s_cmp_eq_u32 s10, 1
	s_cselect_b32 s10, s12, 0
	s_cmp_eq_u32 s9, 0
	s_cselect_b32 s10, 1, s10
	s_and_b32 s8, s8, s10
	s_and_b32 s9, s28, 7
	s_cmp_eq_u32 s9, 0
	s_cselect_b32 s8, s8, 0
	v_mov_b32_e32 v4, 0x20008
	v_mov_b32_e32 v5, s8
	ds_write_b32 v4, v5

.LBB0_411:
	s_andn2_saveexec_b64 s[6:7], s[6:7]
	s_cbranch_execz .LBB0_431
	s_mov_b64 s[6:7], exec
	v_mov_b32_e32 v1, 0x20008
	ds_read_b32 v1, v1
	s_waitcnt lgkmcnt(0)
	s_nop 0
	v_readfirstlane_b32 s32, v1
	s_nop 3
	s_cmp_eq_u32 s32, 0
	s_cbranch_scc1 .Lmy_fullbar_0
	v_mov_b32_e32 v1, 0x2000
	v_mov_b32_e32 v3, 1
	global_atomic_add v1, v3, s[4:5] offset:1024
	buffer_inv sc1
	s_waitcnt vmcnt(0)
	s_branch .LBB0_431
.Lmy_fullbar_0:
	buffer_wbl2 sc1
	buffer_inv sc1
	s_waitcnt lgkmcnt(0)
	s_waitcnt vmcnt(0)
	v_mbcnt_lo_u32_b32 v1, s6, 0
	v_mbcnt_hi_u32_b32 v1, s7, v1
	v_cmp_eq_u32_e32 vcc, 0, v1
	s_and_saveexec_b64 s[10:11], vcc
	s_cbranch_execz .LBB0_414
	s_bcnt1_i32_b64 s6, s[6:7]
	v_mov_b32_e32 v2, 0xfe03000
	v_mov_b32_e32 v3, s6
	global_atomic_add v2, v2, v3, s[26:27] offset:1024 sc0

.LBB0_1003:
	s_andn2_saveexec_b64 s[8:9], s[20:21]
	s_cbranch_execz .LBB0_1023
	s_mov_b64 s[20:21], exec
	v_mov_b32_e32 v1, 0x20008
	ds_read_b32 v1, v1
	s_waitcnt lgkmcnt(0)
	s_nop 0
	v_readfirstlane_b32 s32, v1
	s_nop 3
	s_cmp_eq_u32 s32, 0
	s_cbranch_scc1 .Lmy_fullbar_1
	v_mov_b32_e32 v1, 0x2000
	v_mov_b32_e32 v3, 1
	global_atomic_add v1, v3, s[6:7] offset:1024
	buffer_inv sc1
	s_waitcnt vmcnt(0)
	s_branch .LBB0_1023
.Lmy_fullbar_1:
	buffer_wbl2 sc1
	buffer_inv sc1
	s_waitcnt lgkmcnt(0)
	s_waitcnt vmcnt(0)
	v_mbcnt_lo_u32_b32 v1, s20, 0
	v_mbcnt_hi_u32_b32 v1, s21, v1
	v_cmp_eq_u32_e32 vcc, 0, v1
	s_and_saveexec_b64 s[22:23], vcc
	s_cbranch_execz .LBB0_1006
	s_bcnt1_i32_b64 s3, s[20:21]
	v_mov_b32_e32 v2, 0xfe03000
	v_mov_b32_e32 v3, s3
	global_atomic_add v2, v2, v3, s[26:27] offset:1024 sc0

.LBB0_1111:
	s_andn2_saveexec_b64 s[8:9], s[14:15]
	s_cbranch_execz .LBB0_1131
	s_mov_b64 s[14:15], exec
	v_mov_b32_e32 v1, 0x20008
	ds_read_b32 v1, v1
	s_waitcnt lgkmcnt(0)
	s_nop 0
	v_readfirstlane_b32 s32, v1
	s_nop 3
	s_cmp_eq_u32 s32, 0
	s_cbranch_scc1 .Lmy_fullbar_2
	v_mov_b32_e32 v1, 0x2000
	v_mov_b32_e32 v3, 1
	global_atomic_add v1, v3, s[6:7] offset:1024
	buffer_inv sc1
	s_waitcnt vmcnt(0)
	s_branch .LBB0_1131
.Lmy_fullbar_2:
	buffer_wbl2 sc1
	buffer_inv sc1
	s_waitcnt lgkmcnt(0)
	s_waitcnt vmcnt(0)
	v_mbcnt_lo_u32_b32 v1, s14, 0
	v_mbcnt_hi_u32_b32 v1, s15, v1
	v_cmp_eq_u32_e32 vcc, 0, v1
	s_and_saveexec_b64 s[18:19], vcc
	s_cbranch_execz .LBB0_1114
	s_bcnt1_i32_b64 s3, s[14:15]
	v_mov_b32_e32 v2, 0xfe03000
	v_mov_b32_e32 v3, s3
	global_atomic_add v2, v2, v3, s[26:27] offset:1024 sc0

.LBB0_1273:
	s_andn2_saveexec_b64 s[8:9], s[8:9]
	s_cbranch_execz .LBB0_1293
	s_mov_b64 s[8:9], exec
	v_mov_b32_e32 v1, 0x20008
	ds_read_b32 v1, v1
	s_waitcnt lgkmcnt(0)
	s_nop 0
	v_readfirstlane_b32 s32, v1
	s_nop 3
	s_cmp_eq_u32 s32, 0
	s_cbranch_scc1 .Lmy_fullbar_3
	v_mov_b32_e32 v1, 0x2000
	v_mov_b32_e32 v3, 1
	global_atomic_add v1, v3, s[6:7] offset:1024
	buffer_inv sc1
	s_waitcnt vmcnt(0)
	s_branch .LBB0_1293
.Lmy_fullbar_3:
	buffer_wbl2 sc1
	buffer_inv sc1
	s_waitcnt lgkmcnt(0)
	s_waitcnt vmcnt(0)
	v_mbcnt_lo_u32_b32 v1, s8, 0
	v_mbcnt_hi_u32_b32 v1, s9, v1
	v_cmp_eq_u32_e32 vcc, 0, v1
	s_and_saveexec_b64 s[14:15], vcc
	s_cbranch_execz .LBB0_1276
	s_bcnt1_i32_b64 s3, s[8:9]
	v_mov_b32_e32 v2, 0xfe03000
	v_mov_b32_e32 v3, s3
	global_atomic_add v2, v2, v3, s[26:27] offset:1024 sc0
